# shared V^T of the stick-breaking layers stored in a 32-key tile layout (whole 128-byte lines per V^T tile); producer epilogue switched by layer index, consumer loads re-addressed
# speedup vs baseline: 1.0060x; 1.0060x over previous
.LBB0_175:
	s_cmp_eq_u32 s9, 1
	s_mov_b64 s[68:69], -1
	s_cbranch_scc0 .LBB0_177
	v_readlane_b32 s100, v254, 62
	v_and_b32_e32 v230, 64, v0
	v_mov_b32_e32 v231, 0
	s_nop 1
	s_cmp_lt_u32 s100, 2
	s_cselect_b32 s100, 7, 6
	s_cselect_b32 s101, 0, 1
	s_cselect_b32 s6, 0, 11
	v_lshlrev_b32_e32 v230, s6, v230
	v_and_or_b32 v230, v0, 63, v230
	s_lshl_b32 s6, s52, 8
	s_or_b32 s6, s6, s19
	s_ashr_i32 s12, s6, 6
	v_lshl_add_u32 v130, s11, 10, v164
	s_ashr_i32 s13, s12, 31
	ds_read_b128 v[142:145], v130
	ds_read_b128 v[138:141], v130 offset:16
	ds_read_b128 v[134:137], v130 offset:512
	ds_read_b128 v[130:133], v130 offset:528
	s_lshl_b64 s[20:21], s[12:13], 18
	v_lshl_add_u32 v172, s64, 8, v161
	s_add_u32 s68, s18, s20
	v_ashrrev_i32_e32 v173, 31, v172
	s_addc_u32 s69, s37, s21
	s_or_b32 s12, s12, 2
	v_lshlrev_b64 v[158:159], s100, v[172:173]
	s_waitcnt lgkmcnt(0)
	v_pk_mul_f32 v[170:171], v[128:129], v[144:145]
	v_pk_mul_f32 v[168:169], v[126:127], v[142:143]
	v_pk_mul_f32 v[174:175], v[124:125], v[140:141]
	s_ashr_i32 s13, s12, 31
	v_pk_mul_f32 v[176:177], v[122:123], v[138:139]
	v_cvt_pk_bf16_f32 v168, v168, v169
	v_cvt_pk_bf16_f32 v169, v170, v171
	s_lshl_b64 s[12:13], s[12:13], 18
	v_cvt_pk_bf16_f32 v170, v176, v177
	v_cvt_pk_bf16_f32 v171, v174, v175
	v_lshl_add_u64 v[174:175], s[68:69], 0, v[158:159]
	v_lshl_add_u64 v[174:175], v[174:175], 0, v[230:231]
	s_add_u32 vcc_lo, s18, s12
	global_store_dwordx4 v[174:175], v[168:171], off
	v_pk_mul_f32 v[174:175], v[116:117], v[132:133]
	s_addc_u32 vcc_hi, s37, s13
	v_pk_mul_f32 v[170:171], v[120:121], v[136:137]
	v_pk_mul_f32 v[168:169], v[118:119], v[134:135]
	v_pk_mul_f32 v[176:177], v[114:115], v[130:131]
	v_cvt_pk_bf16_f32 v168, v168, v169
	v_cvt_pk_bf16_f32 v169, v170, v171
	v_pk_mul_f32 v[178:179], v[106:107], v[138:139]
	v_cvt_pk_bf16_f32 v170, v176, v177
	v_cvt_pk_bf16_f32 v171, v174, v175
	v_lshl_add_u64 v[174:175], vcc, 0, v[158:159]
	v_lshl_add_u64 v[174:175], v[174:175], 0, v[230:231]
	global_store_dwordx4 v[174:175], v[168:171], off
	v_pk_mul_f32 v[176:177], v[108:109], v[140:141]
	s_mov_b64 s[12:13], 0x4000
	s_lshr_b32 s12, s12, s101
	v_or_b32_e32 v168, 16, v172
	v_ashrrev_i32_e32 v169, 31, v168
	v_lshlrev_b64 v[174:175], s100, v[168:169]
	v_pk_mul_f32 v[170:171], v[112:113], v[144:145]
	v_pk_mul_f32 v[168:169], v[110:111], v[142:143]
	s_nop 0
	v_cvt_pk_bf16_f32 v168, v168, v169
	v_cvt_pk_bf16_f32 v169, v170, v171
	v_cvt_pk_bf16_f32 v170, v178, v179
	v_cvt_pk_bf16_f32 v171, v176, v177
	v_lshl_add_u64 v[176:177], s[68:69], 0, v[174:175]
	v_lshl_add_u64 v[176:177], v[176:177], 0, v[230:231]
	global_store_dwordx4 v[176:177], v[168:171], off
	v_lshl_add_u64 v[174:175], vcc, 0, v[174:175]
	v_lshl_add_u64 v[174:175], v[174:175], 0, v[230:231]
	v_pk_mul_f32 v[168:169], v[102:103], v[134:135]
	v_pk_mul_f32 v[170:171], v[104:105], v[136:137]
	v_cvt_pk_bf16_f32 v168, v168, v169
	v_pk_mul_f32 v[176:177], v[100:101], v[132:133]
	v_pk_mul_f32 v[178:179], v[98:99], v[130:131]
	v_cvt_pk_bf16_f32 v169, v170, v171
	s_nop 0
	v_cvt_pk_bf16_f32 v170, v178, v179
	v_cvt_pk_bf16_f32 v171, v176, v177
	global_store_dwordx4 v[174:175], v[168:171], off
	v_pk_mul_f32 v[176:177], v[92:93], v[140:141]
	v_pk_mul_f32 v[178:179], v[90:91], v[138:139]
	v_or_b32_e32 v168, 32, v172
	v_ashrrev_i32_e32 v169, 31, v168
	v_lshlrev_b64 v[174:175], s100, v[168:169]
	v_pk_mul_f32 v[170:171], v[96:97], v[144:145]
	v_pk_mul_f32 v[168:169], v[94:95], v[142:143]
	s_nop 0
	v_cvt_pk_bf16_f32 v168, v168, v169
	v_cvt_pk_bf16_f32 v169, v170, v171
	v_cvt_pk_bf16_f32 v170, v178, v179
	v_cvt_pk_bf16_f32 v171, v176, v177
	v_lshl_add_u64 v[176:177], s[68:69], 0, v[174:175]
	v_lshl_add_u64 v[176:177], v[176:177], 0, v[230:231]
	global_store_dwordx4 v[176:177], v[168:171], off
	v_lshl_add_u64 v[174:175], vcc, 0, v[174:175]
	v_lshl_add_u64 v[174:175], v[174:175], 0, v[230:231]
	v_pk_mul_f32 v[168:169], v[86:87], v[134:135]
	v_pk_mul_f32 v[170:171], v[88:89], v[136:137]
	v_cvt_pk_bf16_f32 v168, v168, v169
	v_pk_mul_f32 v[176:177], v[84:85], v[132:133]
	v_pk_mul_f32 v[178:179], v[82:83], v[130:131]
	v_cvt_pk_bf16_f32 v169, v170, v171
	s_nop 0
	v_cvt_pk_bf16_f32 v170, v178, v179
	v_cvt_pk_bf16_f32 v171, v176, v177
	global_store_dwordx4 v[174:175], v[168:171], off
	v_pk_mul_f32 v[174:175], v[76:77], v[140:141]
	v_pk_mul_f32 v[176:177], v[74:75], v[138:139]
	v_or_b32_e32 v168, 48, v172
	v_ashrrev_i32_e32 v169, 31, v168
	v_lshlrev_b64 v[172:173], s100, v[168:169]
	v_pk_mul_f32 v[170:171], v[80:81], v[144:145]
	v_pk_mul_f32 v[168:169], v[78:79], v[142:143]
	s_nop 0
	v_cvt_pk_bf16_f32 v168, v168, v169
	v_cvt_pk_bf16_f32 v169, v170, v171
	v_cvt_pk_bf16_f32 v170, v176, v177
	v_cvt_pk_bf16_f32 v171, v174, v175
	v_lshl_add_u64 v[174:175], s[68:69], 0, v[172:173]
	v_lshl_add_u64 v[174:175], v[174:175], 0, v[230:231]
	global_store_dwordx4 v[174:175], v[168:171], off
	v_lshl_add_u64 v[172:173], vcc, 0, v[172:173]
	v_pk_mul_f32 v[174:175], v[68:69], v[132:133]
	v_pk_mul_f32 v[170:171], v[72:73], v[136:137]
	v_pk_mul_f32 v[168:169], v[70:71], v[134:135]
	v_pk_mul_f32 v[176:177], v[66:67], v[130:131]
	v_cvt_pk_bf16_f32 v168, v168, v169
	v_cvt_pk_bf16_f32 v169, v170, v171
	v_lshl_add_u64 v[172:173], v[172:173], 0, v[230:231]
	v_cvt_pk_bf16_f32 v170, v176, v177
	v_cvt_pk_bf16_f32 v171, v174, v175
	global_store_dwordx4 v[172:173], v[168:171], off
	v_lshl_add_u64 v[172:173], v[158:159], 0, s[12:13]
	v_pk_mul_f32 v[174:175], v[60:61], v[140:141]
	v_pk_mul_f32 v[170:171], v[64:65], v[144:145]
	v_pk_mul_f32 v[168:169], v[62:63], v[142:143]
	v_pk_mul_f32 v[176:177], v[58:59], v[138:139]
	v_cvt_pk_bf16_f32 v168, v168, v169
	v_cvt_pk_bf16_f32 v169, v170, v171
	s_mov_b64 s[12:13], 0x4800
	s_lshr_b32 s12, s12, s101
	v_cvt_pk_bf16_f32 v170, v176, v177
	v_cvt_pk_bf16_f32 v171, v174, v175
	v_lshl_add_u64 v[174:175], s[68:69], 0, v[172:173]
	v_lshl_add_u64 v[174:175], v[174:175], 0, v[230:231]
	global_store_dwordx4 v[174:175], v[168:171], off
	v_lshl_add_u64 v[172:173], vcc, 0, v[172:173]
	v_pk_mul_f32 v[174:175], v[48:49], v[132:133]
	v_pk_mul_f32 v[170:171], v[56:57], v[136:137]
	v_pk_mul_f32 v[168:169], v[54:55], v[134:135]
	v_pk_mul_f32 v[176:177], v[46:47], v[130:131]
	v_cvt_pk_bf16_f32 v168, v168, v169
	v_cvt_pk_bf16_f32 v169, v170, v171
	v_lshl_add_u64 v[172:173], v[172:173], 0, v[230:231]
	v_cvt_pk_bf16_f32 v170, v176, v177
	v_cvt_pk_bf16_f32 v171, v174, v175
	global_store_dwordx4 v[172:173], v[168:171], off
	v_lshl_add_u64 v[172:173], v[158:159], 0, s[12:13]
	v_pk_mul_f32 v[174:175], v[44:45], v[140:141]
	v_pk_mul_f32 v[170:171], v[52:53], v[144:145]
	v_pk_mul_f32 v[168:169], v[50:51], v[142:143]
	v_pk_mul_f32 v[176:177], v[42:43], v[138:139]
	v_cvt_pk_bf16_f32 v168, v168, v169
	v_cvt_pk_bf16_f32 v169, v170, v171
	s_mov_b64 s[12:13], 0x5000
	s_lshr_b32 s12, s12, s101
	v_cvt_pk_bf16_f32 v170, v176, v177
	v_cvt_pk_bf16_f32 v171, v174, v175
	v_lshl_add_u64 v[174:175], s[68:69], 0, v[172:173]
	v_lshl_add_u64 v[174:175], v[174:175], 0, v[230:231]
	global_store_dwordx4 v[174:175], v[168:171], off
	v_lshl_add_u64 v[172:173], vcc, 0, v[172:173]
	v_pk_mul_f32 v[174:175], v[32:33], v[132:133]
	v_pk_mul_f32 v[170:171], v[40:41], v[136:137]
	v_pk_mul_f32 v[168:169], v[38:39], v[134:135]
	v_pk_mul_f32 v[176:177], v[30:31], v[130:131]
	v_cvt_pk_bf16_f32 v168, v168, v169
	v_cvt_pk_bf16_f32 v169, v170, v171
	v_lshl_add_u64 v[172:173], v[172:173], 0, v[230:231]
	v_cvt_pk_bf16_f32 v170, v176, v177
	v_cvt_pk_bf16_f32 v171, v174, v175
	global_store_dwordx4 v[172:173], v[168:171], off
	v_lshl_add_u64 v[172:173], v[158:159], 0, s[12:13]
	v_pk_mul_f32 v[174:175], v[28:29], v[140:141]
	v_pk_mul_f32 v[170:171], v[36:37], v[144:145]
	v_pk_mul_f32 v[168:169], v[34:35], v[142:143]
	v_pk_mul_f32 v[176:177], v[26:27], v[138:139]
	v_cvt_pk_bf16_f32 v168, v168, v169
	v_cvt_pk_bf16_f32 v169, v170, v171
	s_mov_b64 s[12:13], 0x5800
	s_lshr_b32 s12, s12, s101
	v_cvt_pk_bf16_f32 v170, v176, v177
	v_cvt_pk_bf16_f32 v171, v174, v175
	v_lshl_add_u64 v[174:175], s[68:69], 0, v[172:173]
	v_lshl_add_u64 v[174:175], v[174:175], 0, v[230:231]
	global_store_dwordx4 v[174:175], v[168:171], off
	v_lshl_add_u64 v[172:173], vcc, 0, v[172:173]
	v_lshl_add_u64 v[172:173], v[172:173], 0, v[230:231]
	v_pk_mul_f32 v[168:169], v[22:23], v[134:135]
	v_pk_mul_f32 v[170:171], v[24:25], v[136:137]
	v_cvt_pk_bf16_f32 v168, v168, v169
	v_lshl_add_u64 v[158:159], v[158:159], 0, s[12:13]
	v_cvt_pk_bf16_f32 v169, v170, v171
	v_pk_mul_f32 v[142:143], v[14:15], v[142:143]
	v_pk_mul_f32 v[174:175], v[20:21], v[132:133]
	v_pk_mul_f32 v[176:177], v[18:19], v[130:131]
	v_pk_mul_f32 v[144:145], v[16:17], v[144:145]
	v_cvt_pk_bf16_f32 v170, v176, v177
	v_cvt_pk_bf16_f32 v171, v174, v175
	global_store_dwordx4 v[172:173], v[168:171], off
	v_pk_mul_f32 v[134:135], v[6:7], v[134:135]
	v_pk_mul_f32 v[136:137], v[8:9], v[136:137]
	v_pk_mul_f32 v[168:169], v[12:13], v[140:141]
	v_pk_mul_f32 v[140:141], v[10:11], v[138:139]
	v_cvt_pk_bf16_f32 v138, v142, v143
	v_lshl_add_u64 v[142:143], s[68:69], 0, v[158:159]
	v_cvt_pk_bf16_f32 v139, v144, v145
	v_lshl_add_u64 v[142:143], v[142:143], 0, v[230:231]
	v_cvt_pk_bf16_f32 v140, v140, v141
	v_cvt_pk_bf16_f32 v141, v168, v169
	global_store_dwordx4 v[142:143], v[138:141], off
	s_mov_b64 s[68:69], 0
	s_nop 0
	v_pk_mul_f32 v[138:139], v[4:5], v[132:133]
	v_pk_mul_f32 v[132:133], v[2:3], v[130:131]
	v_cvt_pk_bf16_f32 v130, v134, v135
	v_lshl_add_u64 v[134:135], vcc, 0, v[158:159]
	v_lshl_add_u64 v[134:135], v[134:135], 0, v[230:231]
	v_cvt_pk_bf16_f32 v131, v136, v137
	v_cvt_pk_bf16_f32 v132, v132, v133
	v_cvt_pk_bf16_f32 v133, v138, v139
	global_store_dwordx4 v[134:135], v[130:133], off

.LBB0_247:
	s_and_b32 s27, s15, 0xff
	s_ashr_i32 s42, s15, 12
	v_mov_b32_e32 v38, v208
	s_ashr_i32 s43, s42, 31
	v_and_b32_e32 v78, 31, v38
	s_lshl_b32 s8, s27, 5
	s_lshl_b64 s[0:1], s[42:43], 13
	v_or_b32_e32 v79, s8, v78
	v_or_b32_e32 v146, s0, v79
	v_mov_b32_e32 v147, s1
	s_lshr_b32 s1, s15, 1
	v_lshlrev_b64 v[2:3], 12, v[146:147]
	s_and_b32 s9, s1, 0x780
	v_bfe_u32 v68, v38, 5, 1
	v_lshl_add_u64 v[2:3], s[4:5], 0, v[2:3]
	s_lshl_b32 s40, s9, 1
	s_mov_b32 s41, s85
	v_lshl_add_u64 v[2:3], v[2:3], 0, s[40:41]
	v_lshlrev_b32_e32 v0, 4, v68
	v_lshl_add_u64 v[2:3], v[2:3], 0, v[0:1]
	global_load_dwordx4 v[82:85], v[2:3], off
	global_load_dwordx4 v[86:89], v[2:3], off offset:32
	global_load_dwordx4 v[90:93], v[2:3], off offset:64
	global_load_dwordx4 v[94:97], v[2:3], off offset:96
	global_load_dwordx4 v[98:101], v[2:3], off offset:128
	global_load_dwordx4 v[102:105], v[2:3], off offset:160
	global_load_dwordx4 v[106:109], v[2:3], off offset:192
	global_load_dwordx4 v[110:113], v[2:3], off offset:224
	s_lshl_b32 s10, s42, 7
	v_bfe_u32 v69, v38, 4, 2
	s_ashr_i32 s11, s10, 31
	v_lshrrev_b32_e32 v3, 1, v38
	v_or_b32_e32 v2, s0, v69
	s_lshl_b64 s[0:1], s[10:11], 11
	v_and_b32_e32 v37, 4, v3
	v_mov_b32_e32 v3, v147
	v_readlane_b32 s10, v252, 51
	v_lshlrev_b64 v[2:3], 12, v[2:3]
	v_readlane_b32 s11, v252, 52
	v_lshlrev_b32_e32 v0, 1, v38
	v_lshlrev_b32_e32 v71, 4, v38
	v_lshl_add_u64 v[2:3], s[10:11], 0, v[2:3]
	v_and_b32_e32 v36, 8, v0
	v_lshl_add_u64 v[2:3], v[2:3], 0, s[40:41]
	v_and_b32_e32 v0, 0xf0, v71
	s_lshl_b32 s84, s27, 17
	v_lshl_add_u64 v[150:151], v[2:3], 0, v[0:1]
	v_lshl_add_u64 v[30:31], v[150:151], 0, s[84:85]
	v_add_co_u32_e32 v6, vcc, s81, v30
	v_bfe_u32 v70, v38, 2, 4
	s_nop 0
	v_addc_co_u32_e32 v7, vcc, 0, v31, vcc
	v_add_co_u32_e32 v10, vcc, s82, v30
	v_and_b32_e32 v34, 19, v38
	s_nop 0
	v_addc_co_u32_e32 v11, vcc, 0, v31, vcc
	v_add_co_u32_e32 v14, vcc, s76, v30
	v_or_b32_e32 v48, s0, v70
	s_nop 0
	v_addc_co_u32_e32 v15, vcc, 0, v31, vcc
	v_add_co_u32_e32 v18, vcc, s70, v30
	v_mov_b32_e32 v35, s1
	s_nop 0
	v_addc_co_u32_e32 v19, vcc, 0, v31, vcc
	v_add_co_u32_e32 v22, vcc, s80, v30
	v_or3_b32 v76, v37, v34, v36
	s_nop 0
	v_addc_co_u32_e32 v23, vcc, 0, v31, vcc
	v_add_co_u32_e32 v26, vcc, s71, v30
	v_or_b32_e32 v34, s9, v48
	s_nop 0
	v_addc_co_u32_e32 v27, vcc, 0, v31, vcc
	v_readlane_b32 s0, v252, 53
	v_xor_b32_e32 v0, v69, v38
	v_or_b32_e32 v212, s9, v70
	v_lshlrev_b64 v[34:35], 7, v[34:35]
	v_lshlrev_b32_e32 v212, 6, v212
	s_nop 0
	v_sub_co_u32_e32 v34, vcc, v34, v212
	s_nop 1
	v_subbrev_co_u32_e32 v35, vcc, 0, v35, vcc
	v_readlane_b32 s1, v252, 54
	v_lshlrev_b32_e32 v77, 4, v0
	v_and_b32_e32 v0, 48, v71
	v_lshl_add_u64 v[34:35], s[0:1], 0, v[34:35]
	s_lshl_b32 s6, s15, 6
	v_lshl_add_u64 v[152:153], v[34:35], 0, v[0:1]
	s_waitcnt vmcnt(7)
	s_waitcnt vmcnt(6)
	s_waitcnt vmcnt(5)
	s_waitcnt vmcnt(4)
	s_waitcnt vmcnt(3)
	s_waitcnt vmcnt(2)
	s_waitcnt vmcnt(1)
	s_waitcnt vmcnt(0)
	global_load_dwordx4 v[2:5], v[30:31], off
	s_nop 0
	global_load_dwordx4 v[6:9], v[6:7], off
	s_nop 0
	global_load_dwordx4 v[10:13], v[10:11], off
	s_nop 0
	global_load_dwordx4 v[14:17], v[14:15], off
	s_nop 0
	global_load_dwordx4 v[18:21], v[18:19], off
	s_nop 0
	global_load_dwordx4 v[22:25], v[22:23], off
	v_add_co_u32_e32 v30, vcc, s83, v30
	global_load_dwordx4 v[26:29], v[26:27], off
	s_nop 0
	v_addc_co_u32_e32 v31, vcc, 0, v31, vcc
	global_load_dwordx4 v[30:33], v[30:31], off
	s_and_b32 s84, s84, 0x1fc0000
	v_lshl_add_u64 v[34:35], v[152:153], 0, s[84:85]
	s_and_b32 s84, s6, 64
	s_lshl_b32 s84, s84, 11
	v_lshl_add_u64 v[52:53], v[34:35], 0, s[84:85]
	v_add_co_u32_e32 v48, vcc, s77, v52
	v_or_b32_e32 v40, 4, v69
	s_nop 0
	v_addc_co_u32_e32 v49, vcc, 0, v53, vcc
	v_bitop3_b32 v41, v69, v38, 4 bitop3:0x36
	v_or_b32_e32 v42, 8, v69
	v_bitop3_b32 v43, v69, v38, 8 bitop3:0x36
	v_or_b32_e32 v44, 12, v69
	v_bitop3_b32 v45, v69, v38, 12 bitop3:0x36
	v_or_b32_e32 v46, 20, v69
	v_bitop3_b32 v47, v69, v38, 20 bitop3:0x36
	v_add_co_u32_e32 v56, vcc, s77, v52
	v_lshl_add_u32 v80, v40, 8, s33
	v_lshlrev_b32_e32 v81, 4, v41
	v_lshl_add_u32 v114, v42, 8, s33
	v_lshlrev_b32_e32 v115, 4, v43
	v_lshl_add_u32 v116, v44, 8, s33
	v_lshlrev_b32_e32 v117, 4, v45
	v_lshl_add_u32 v118, v46, 8, s33
	v_lshlrev_b32_e32 v119, 4, v47
	v_addc_co_u32_e32 v57, vcc, 0, v53, vcc
	global_load_dwordx4 v[34:37], v[52:53], off
	global_load_dwordx4 v[40:43], v[52:53], off offset:1024
	global_load_dwordx4 v[44:47], v[52:53], off offset:2048
	s_nop 0
	global_load_dwordx4 v[48:51], v[52:53], off offset:3072
	v_add_co_u32_e32 v64, vcc, s77, v52
	v_lshl_add_u32 v75, v69, 8, s33
	s_nop 0
	v_addc_co_u32_e32 v65, vcc, 0, v53, vcc
	global_load_dwordx4 v[52:55], v[56:57], off
	s_nop 0
	global_load_dwordx4 v[56:59], v[56:57], off offset:1024
	s_nop 0
	global_load_dwordx4 v[60:63], v[64:65], off offset:2048
	s_nop 0
	global_load_dwordx4 v[64:67], v[64:65], off offset:3072
	v_and_b32_e32 v0, 0xf0, v77
	v_and_b32_e32 v77, 0xf0, v81
	v_and_b32_e32 v81, 0xf0, v115
	v_and_b32_e32 v115, 0xf0, v117
	v_and_b32_e32 v117, 0xf0, v119
	v_add_u32_e32 v0, v75, v0
	v_add_u32_e32 v149, v80, v77
	v_add_u32_e32 v174, v114, v81
	v_add_u32_e32 v175, v116, v115
	v_add_u32_e32 v176, v118, v117
	v_bitop3_b32 v121, v76, v68, 15 bitop3:0x6c
	v_lshlrev_b32_e32 v120, 8, v76
	v_or_b32_e32 v72, 2, v68
	v_bitop3_b32 v72, v76, v72, 15 bitop3:0x6c
	v_or_b32_e32 v73, 4, v68
	v_bitop3_b32 v73, v76, v73, 15 bitop3:0x6c
	v_or_b32_e32 v74, 6, v68
	v_lshlrev_b32_e32 v148, 3, v68
	v_and_b32_e32 v39, 63, v38
	v_cmp_lt_u32_e64 s[68:69], v148, v78
	s_waitcnt vmcnt(15)
	ds_write_b128 v0, v[2:5]
	s_waitcnt vmcnt(14)
	ds_write_b128 v149, v[6:9]
	s_waitcnt vmcnt(13)
	ds_write_b128 v174, v[10:13]
	s_waitcnt vmcnt(12)
	ds_write_b128 v175, v[14:17]
	s_waitcnt vmcnt(11)
	ds_write_b128 v0, v[18:21] offset:4096
	s_waitcnt vmcnt(10)
	ds_write_b128 v176, v[22:25]
	v_bitop3_b32 v3, v69, v38, 24 bitop3:0x36
	v_or_b32_e32 v2, 24, v69
	v_lshlrev_b32_e32 v3, 4, v3
	v_lshl_add_u32 v2, v2, 8, s33
	v_and_b32_e32 v3, 0xf0, v3
	v_add_u32_e32 v177, v2, v3
	v_bitop3_b32 v3, v69, v38, 28 bitop3:0x36
	v_or_b32_e32 v2, 28, v69
	v_lshlrev_b32_e32 v3, 4, v3
	v_lshl_add_u32 v2, v2, 8, s33
	v_and_b32_e32 v3, 0xf0, v3
	v_add_u32_e32 v178, v2, v3
	v_lshl_add_u32 v2, v121, 4, s33
	s_waitcnt vmcnt(9)
	ds_write_b128 v177, v[26:29]
	s_waitcnt vmcnt(8)
	ds_write_b128 v178, v[30:33]
	v_add_u32_e32 v179, v2, v120
	ds_read_b128 v[2:5], v179
	v_or_b32_e32 v6, 8, v68
	v_bitop3_b32 v27, v76, v6, 15 bitop3:0x6c
	v_or_b32_e32 v6, 10, v68
	v_bitop3_b32 v28, v76, v6, 15 bitop3:0x6c
	v_lshl_add_u32 v6, v72, 4, s33
	v_add_u32_e32 v180, v6, v120
	ds_read_b128 v[18:21], v180
	s_waitcnt lgkmcnt(1)
	v_mfma_f32_32x32x16_bf16 v[2:17], v[2:5], v[82:85], 0
	v_or_b32_e32 v22, 12, v68
	v_bitop3_b32 v29, v76, v22, 15 bitop3:0x6c
	v_or_b32_e32 v22, 14, v68
	v_bitop3_b32 v30, v76, v22, 15 bitop3:0x6c
	v_lshl_add_u32 v22, v73, 4, s33
	v_add_u32_e32 v181, v22, v120
	ds_read_b128 v[22:25], v181
	s_waitcnt lgkmcnt(1)
	v_mfma_f32_32x32x16_bf16 v[2:17], v[18:21], v[86:89], v[2:17]
	v_bitop3_b32 v26, v76, v74, 15 bitop3:0x6c
	v_lshrrev_b32_e32 v18, 2, v38
	v_bitop3_b32 v33, v68, v18, 3 bitop3:0x78
	v_lshl_add_u32 v18, v26, 4, s33
	v_add_u32_e32 v182, v18, v120
	ds_read_b128 v[18:21], v182
	v_bfe_u32 v32, v38, 2, 2
	s_waitcnt lgkmcnt(1)
	v_mfma_f32_32x32x16_bf16 v[2:17], v[22:25], v[90:93], v[2:17]
	v_lshl_add_u32 v22, v70, 6, s33
	v_bitop3_b32 v23, v71, 48, v38 bitop3:0x48
	v_add_u32_e32 v183, v22, v23
	v_lshl_add_u32 v22, v27, 4, s33
	v_add_u32_e32 v184, v22, v120
	ds_read_b128 v[22:25], v184
	s_waitcnt vmcnt(7)
	ds_write_b128 v183, v[34:37] offset:8192
	s_waitcnt vmcnt(6)
	ds_write_b128 v183, v[40:43] offset:9216
	s_waitcnt vmcnt(5)
	ds_write_b128 v183, v[44:47] offset:10240
	s_waitcnt vmcnt(4)
	ds_write_b128 v183, v[48:51] offset:11264
	s_waitcnt lgkmcnt(5)
	v_mfma_f32_32x32x16_bf16 v[2:17], v[18:21], v[94:97], v[2:17]
	v_lshl_add_u32 v18, v28, 4, s33
	v_add_u32_e32 v185, v18, v120
	ds_read_b128 v[18:21], v185
	s_waitcnt vmcnt(3)
	ds_write_b128 v183, v[52:55] offset:12288
	s_waitcnt vmcnt(2)
	ds_write_b128 v183, v[56:59] offset:13312
	s_waitcnt vmcnt(1)
	ds_write_b128 v183, v[60:63] offset:14336
	s_waitcnt vmcnt(0)
	ds_write_b128 v183, v[64:67] offset:15360
	v_or_b32_e32 v38, s8, v148
	v_lshlrev_b32_e32 v31, 6, v78
	v_bitop3_b32 v26, v68, v32, 2 bitop3:0x36
	s_waitcnt lgkmcnt(9)
	v_mfma_f32_32x32x16_bf16 v[2:17], v[22:25], v[98:101], v[2:17]
	v_lshl_add_u32 v22, v29, 4, s33
	v_add_u32_e32 v186, v22, v120
	ds_read_b128 v[22:25], v186
	s_waitcnt lgkmcnt(5)
	v_mfma_f32_32x32x16_bf16 v[2:17], v[18:21], v[102:105], v[2:17]
	v_lshl_add_u32 v18, v30, 4, s33
	v_add_u32_e32 v187, v18, v120
	ds_read_b128 v[40:43], v187
	v_lshl_or_b32 v18, v33, 4, v31
	v_add_u32_e32 v188, s33, v18
	v_lshl_or_b32 v18, v26, 4, v31
	v_add_u32_e32 v189, s33, v18
	s_waitcnt lgkmcnt(1)
	v_mfma_f32_32x32x16_bf16 v[2:17], v[22:25], v[106:109], v[2:17]
	ds_read_b128 v[34:37], v188 offset:8192
	ds_read_b128 v[18:21], v188 offset:10240
	ds_read_b128 v[30:33], v189 offset:8192
	ds_read_b128 v[22:25], v189 offset:10240
	ds_read_b128 v[26:29], v188 offset:12288
	ds_read_b128 v[70:73], v188 offset:14336
	ds_read_b128 v[74:77], v189 offset:12288
	ds_read_b128 v[66:69], v189 offset:14336
	s_waitcnt lgkmcnt(8)
	v_mfma_f32_32x32x16_bf16 v[2:17], v[40:43], v[110:113], v[2:17]
	v_or_b32_e32 v41, 22, v38
	v_cmp_lt_u32_e32 vcc, v41, v79
	v_or_b32_e32 v41, 21, v38
	v_cmp_lt_u32_e64 s[0:1], v41, v79
	v_or_b32_e32 v41, 20, v38
	v_cmp_lt_u32_e64 s[42:43], v41, v79
	v_or_b32_e32 v41, 19, v38
	v_cmp_lt_u32_e64 s[44:45], v41, v79
	v_or_b32_e32 v41, 18, v38
	v_cmp_lt_u32_e64 s[46:47], v41, v79
	v_or_b32_e32 v41, 17, v38
	v_cmp_lt_u32_e64 s[50:51], v41, v79
	v_or_b32_e32 v41, 16, v38
	v_cmp_lt_u32_e64 s[52:53], v41, v79
	v_or_b32_e32 v41, 7, v38
	v_cmp_lt_u32_e64 s[54:55], v41, v79
	v_or_b32_e32 v41, 6, v38
	v_cmp_lt_u32_e64 s[56:57], v41, v79
	v_or_b32_e32 v41, 5, v38
	v_or_b32_e32 v40, 23, v38
	v_cmp_lt_u32_e64 s[58:59], v41, v79
	v_or_b32_e32 v41, 4, v38
	v_cmp_lt_u32_e64 s[60:61], v41, v79
	v_or_b32_e32 v41, 3, v38
	v_cndmask_b32_e64 v42, v211, v2, s[68:69]
	v_cmp_lt_u32_e64 s[68:69], v40, v79
	v_cmp_lt_u32_e64 s[62:63], v41, v79
	v_or_b32_e32 v41, 2, v38
	s_or_b64 vcc, s[68:69], vcc
	v_cmp_lt_u32_e64 s[64:65], v41, v79
	v_cndmask_b32_e32 v41, v211, v16, vcc
	s_or_b64 vcc, vcc, s[0:1]
	v_or_b32_e32 v38, 1, v38
	v_cndmask_b32_e32 v15, v211, v15, vcc
	s_or_b64 vcc, vcc, s[42:43]
	v_cmp_lt_u32_e64 s[66:67], v38, v79
	v_cndmask_b32_e32 v38, v211, v14, vcc
	s_or_b64 vcc, vcc, s[44:45]
	v_cndmask_b32_e32 v16, v211, v13, vcc
	s_or_b64 vcc, vcc, s[46:47]
	v_cndmask_b32_e32 v14, v211, v12, vcc
	s_or_b64 vcc, vcc, s[50:51]
	v_cndmask_b32_e32 v12, v211, v11, vcc
	s_or_b64 vcc, vcc, s[52:53]
	v_cndmask_b32_e32 v2, v211, v10, vcc
	s_or_b64 vcc, vcc, s[54:55]
	v_cndmask_b32_e32 v9, v211, v9, vcc
	s_or_b64 vcc, vcc, s[56:57]
	v_cndmask_b32_e32 v8, v211, v8, vcc
	s_or_b64 vcc, vcc, s[58:59]
	v_cndmask_b32_e32 v10, v211, v7, vcc
	s_or_b64 vcc, vcc, s[60:61]
	v_cndmask_b32_e32 v6, v211, v6, vcc
	s_or_b64 vcc, vcc, s[62:63]
	v_cndmask_b32_e32 v44, v211, v5, vcc
	v_mul_f32_e64 v5, |v42|, s79
	v_exp_f32_e32 v5, v5
	s_or_b64 vcc, vcc, s[64:65]
	v_cndmask_b32_e32 v4, v211, v4, vcc
	s_or_b64 vcc, vcc, s[66:67]
	v_cndmask_b32_e32 v46, v211, v3, vcc
	v_max_f32_e32 v3, v42, v42
	v_max_f32_e32 v48, 0, v3
	v_add_f32_e32 v3, 1.0, v5
	v_mul_f32_e64 v5, |v46|, s79
	v_exp_f32_e32 v5, v5
	v_log_f32_e32 v50, v3
	v_max_f32_e32 v3, v46, v46
	v_max_f32_e32 v49, 0, v3
	v_add_f32_e32 v3, 1.0, v5
	v_mul_f32_e64 v5, |v4|, s79
	v_exp_f32_e32 v5, v5
	v_log_f32_e32 v51, v3
	v_max_f32_e32 v3, v4, v4
	v_max_f32_e32 v52, 0, v3
	v_add_f32_e32 v3, 1.0, v5
	v_mul_f32_e64 v5, |v44|, s79
	v_exp_f32_e32 v5, v5
	v_log_f32_e32 v54, v3
	v_max_f32_e32 v3, v44, v44
	v_max_f32_e32 v53, 0, v3
	v_add_f32_e32 v3, 1.0, v5
	v_mul_f32_e64 v5, |v6|, s79
	v_exp_f32_e32 v5, v5
	v_log_f32_e32 v55, v3
	v_max_f32_e32 v3, v6, v6
	v_max_f32_e32 v56, 0, v3
	v_add_f32_e32 v3, 1.0, v5
	v_mul_f32_e64 v5, |v10|, s79
	v_exp_f32_e32 v5, v5
	v_log_f32_e32 v58, v3
	v_max_f32_e32 v3, v10, v10
	v_max_f32_e32 v57, 0, v3
	v_add_f32_e32 v3, 1.0, v5
	v_mul_f32_e64 v5, |v8|, s79
	v_exp_f32_e32 v5, v5
	v_log_f32_e32 v59, v3
	v_max_f32_e32 v3, v8, v8
	v_max_f32_e32 v60, 0, v3
	v_add_f32_e32 v3, 1.0, v5
	v_mul_f32_e64 v5, |v9|, s79
	v_exp_f32_e32 v5, v5
	v_log_f32_e32 v62, v3
	v_max_f32_e32 v3, v9, v9
	v_max_f32_e32 v61, 0, v3
	v_add_f32_e32 v3, 1.0, v5
	v_mul_f32_e64 v5, |v2|, s79
	v_exp_f32_e32 v5, v5
	v_log_f32_e32 v63, v3
	v_max_f32_e32 v3, v2, v2
	v_max_f32_e32 v64, 0, v3
	v_add_f32_e32 v3, 1.0, v5
	v_mul_f32_e64 v5, |v12|, s79
	v_exp_f32_e32 v5, v5
	v_log_f32_e32 v78, v3
	v_max_f32_e32 v3, v12, v12
	v_max_f32_e32 v65, 0, v3
	v_add_f32_e32 v3, 1.0, v5
	v_mul_f32_e64 v5, |v14|, s79
	v_exp_f32_e32 v5, v5
	v_log_f32_e32 v79, v3
	v_max_f32_e32 v3, v14, v14
	v_max_f32_e32 v80, 0, v3
	v_add_f32_e32 v3, 1.0, v5
	v_mul_f32_e64 v5, |v16|, s79
	v_exp_f32_e32 v5, v5
	v_log_f32_e32 v114, v3
	v_max_f32_e32 v3, v16, v16
	v_max_f32_e32 v81, 0, v3
	v_add_f32_e32 v3, 1.0, v5
	v_mul_f32_e64 v5, |v38|, s79
	v_exp_f32_e32 v5, v5
	v_log_f32_e32 v115, v3
	v_max_f32_e32 v3, v38, v38
	v_max_f32_e32 v116, 0, v3
	v_add_f32_e32 v3, 1.0, v5
	v_mul_f32_e64 v5, |v15|, s79
	v_exp_f32_e32 v5, v5
	v_log_f32_e32 v118, v3
	v_max_f32_e32 v3, v15, v15
	v_max_f32_e32 v117, 0, v3
	v_add_f32_e32 v3, 1.0, v5
	v_cndmask_b32_e64 v17, v211, v17, s[68:69]
	v_log_f32_e32 v119, v3
	v_mul_f32_e64 v3, |v41|, s79
	v_exp_f32_e32 v3, v3
	v_mul_f32_e64 v5, |v17|, s79
	v_exp_f32_e32 v5, v5
	v_pk_fma_f32 v[64:65], v[78:79], s[74:75], v[64:65] op_sel_hi:[1,0,1]
	v_add_f32_e32 v3, 1.0, v3
	v_log_f32_e32 v121, v3
	v_add_f32_e32 v3, 1.0, v5
	v_log_f32_e32 v120, v3
	v_pk_fma_f32 v[80:81], v[114:115], s[74:75], v[80:81] op_sel_hi:[1,0,1]
	v_sub_f32_e64 v5, -v64, v65
	v_sub_f32_e32 v5, v5, v80
	v_max_f32_e32 v7, v41, v41
	v_max_f32_e32 v3, v17, v17
	v_pk_fma_f32 v[116:117], v[118:119], s[74:75], v[116:117] op_sel_hi:[1,0,1]
	v_sub_f32_e32 v5, v5, v81
	v_max_f32_e32 v123, 0, v7
	v_max_f32_e32 v122, 0, v3
	v_sub_f32_e32 v5, v5, v116
	v_pk_fma_f32 v[120:121], v[120:121], s[74:75], v[122:123] op_sel_hi:[1,0,1]
	v_sub_f32_e32 v5, v5, v117
	v_sub_f32_e32 v5, v5, v121
	v_sub_f32_e32 v123, v5, v120
	v_mov_b32_e32 v5, v123
	v_mov_b32_e32 v7, v123
	s_nop 1
	v_permlane32_swap_b32_e32 v5, v7
	v_pk_fma_f32 v[48:49], v[50:51], s[74:75], v[48:49] op_sel_hi:[1,0,1]
	v_cndmask_b32_e64 v122, v5, v7, s[38:39]
	v_pk_fma_f32 v[52:53], v[54:55], s[74:75], v[52:53] op_sel_hi:[1,0,1]
	v_sub_f32_e64 v7, -v48, v49
	v_sub_f32_e32 v7, v7, v52
	v_pk_fma_f32 v[56:57], v[58:59], s[74:75], v[56:57] op_sel_hi:[1,0,1]
	v_sub_f32_e32 v7, v7, v53
	v_sub_f32_e32 v7, v7, v56
	v_pk_fma_f32 v[60:61], v[62:63], s[74:75], v[60:61] op_sel_hi:[1,0,1]
	v_sub_f32_e32 v7, v7, v57
	v_sub_f32_e32 v7, v7, v60
	v_sub_f32_e32 v125, v7, v61
	v_sub_f32_e32 v5, v9, v61
	v_mov_b32_e32 v7, v125
	v_mov_b32_e32 v9, v125
	s_nop 1
	v_permlane32_swap_b32_e32 v7, v9
	v_cndmask_b32_e64 v124, v7, v9, s[38:39]
	v_add_f32_e32 v7, v123, v124
	v_cmp_gt_u32_e64 s[42:43], 32, v39
	v_pk_mov_b32 v[58:59], v[56:57], v[60:61] op_sel:[1,0]
	v_pk_mov_b32 v[54:55], v[52:53], v[56:57] op_sel:[1,0]
	v_cndmask_b32_e64 v7, v123, v7, s[42:43]
	v_add_f32_e32 v7, v7, v122
	v_add_f32_e32 v9, 0, v7
	v_add_f32_e32 v5, v5, v9
	v_mul_f32_e32 v5, 0x3fb8aa3b, v5
	v_pk_add_f32 v[8:9], v[8:9], v[60:61] neg_lo:[0,1] neg_hi:[0,1]
	v_exp_f32_e32 v50, v5
	v_add_f32_e32 v5, v8, v9
	v_mov_b32_e32 v11, v9
	v_mul_f32_e32 v5, 0x3fb8aa3b, v5
	v_pk_add_f32 v[8:9], v[10:11], v[58:59] neg_lo:[0,1] neg_hi:[0,1]
	v_exp_f32_e32 v51, v5
	v_add_f32_e32 v5, v8, v9
	v_mov_b32_e32 v7, v9
	v_mul_f32_e32 v5, 0x3fb8aa3b, v5
	v_pk_add_f32 v[6:7], v[6:7], v[56:57] neg_lo:[0,1] neg_hi:[0,1]
	v_exp_f32_e32 v8, v5
	v_add_f32_e32 v5, v6, v7
	v_mov_b32_e32 v45, v7
	v_mul_f32_e32 v5, 0x3fb8aa3b, v5
	v_pk_add_f32 v[6:7], v[44:45], v[54:55] neg_lo:[0,1] neg_hi:[0,1]
	v_exp_f32_e32 v9, v5
	v_add_f32_e32 v5, v6, v7
	v_mul_f32_e32 v5, 0x3fb8aa3b, v5
	v_exp_f32_e32 v6, v5
	v_mov_b32_e32 v5, v7
	v_pk_add_f32 v[4:5], v[4:5], v[52:53] neg_lo:[0,1] neg_hi:[0,1]
	v_sub_f32_e32 v3, v17, v120
	v_add_f32_e32 v4, v4, v5
	v_mul_f32_e32 v4, 0x3fb8aa3b, v4
	v_exp_f32_e32 v7, v4
	v_mov_b32_e32 v47, v5
	v_pk_mov_b32 v[4:5], v[48:49], v[52:53] op_sel:[1,0]
	v_mov_b32_e32 v118, v117
	v_pk_add_f32 v[4:5], v[46:47], v[4:5] neg_lo:[0,1] neg_hi:[0,1]
	v_mov_b32_e32 v119, v121
	v_add_f32_e32 v4, v4, v5
	v_mul_f32_e32 v4, 0x3fb8aa3b, v4
	v_mov_b32_e32 v43, v5
	v_exp_f32_e32 v10, v4
	v_pk_add_f32 v[4:5], v[42:43], v[48:49] neg_lo:[0,1] neg_hi:[0,1]
	v_pk_mov_b32 v[114:115], v[80:81], v[116:117] op_sel:[1,0]
	v_add_f32_e32 v4, v4, v5
	v_mul_f32_e32 v4, 0x3fb8aa3b, v4
	v_exp_f32_e32 v11, v4
	v_add_f32_e32 v4, 0, v122
	v_cndmask_b32_e64 v40, 0, v4, s[42:43]
	v_add_f32_e32 v3, v40, v3
	v_mul_f32_e32 v3, 0x3fb8aa3b, v3
	v_pk_add_f32 v[4:5], v[40:41], v[120:121] neg_lo:[0,1] neg_hi:[0,1]
	v_exp_f32_e32 v42, v3
	v_add_f32_e32 v3, v4, v5
	v_pk_mov_b32 v[4:5], v[14:15], v[4:5] op_sel:[1,0]
	v_mul_f32_e32 v40, 0x3fb8aa3b, v3
	v_pk_add_f32 v[4:5], v[4:5], v[118:119] neg_lo:[0,1] neg_hi:[0,1]
	s_nop 0
	v_mov_b32_e32 v39, v5
	v_add_f32_e32 v3, v4, v5
	v_pk_add_f32 v[4:5], v[38:39], v[116:117] neg_lo:[0,1] neg_hi:[0,1]
	v_mul_f32_e32 v3, 0x3fb8aa3b, v3
	v_mov_b32_e32 v17, v5
	v_exp_f32_e32 v41, v3
	v_add_f32_e32 v3, v4, v5
	v_pk_add_f32 v[4:5], v[16:17], v[114:115] neg_lo:[0,1] neg_hi:[0,1]
	v_mul_f32_e32 v38, 0x3fb8aa3b, v3
	v_add_f32_e32 v3, v4, v5
	v_mov_b32_e32 v15, v5
	v_mul_f32_e32 v3, 0x3fb8aa3b, v3
	v_pk_add_f32 v[4:5], v[14:15], v[80:81] neg_lo:[0,1] neg_hi:[0,1]
	v_exp_f32_e32 v16, v3
	v_add_f32_e32 v3, v4, v5
	v_mov_b32_e32 v13, v5
	v_pk_mov_b32 v[4:5], v[64:65], v[80:81] op_sel:[1,0]
	v_mul_f32_e32 v14, 0x3fb8aa3b, v3
	v_pk_add_f32 v[4:5], v[12:13], v[4:5] neg_lo:[0,1] neg_hi:[0,1]
	s_nop 0
	v_add_f32_e32 v3, v4, v5
	v_mul_f32_e32 v3, 0x3fb8aa3b, v3
	v_exp_f32_e32 v12, v3
	v_mov_b32_e32 v3, v5
	v_pk_add_f32 v[2:3], v[2:3], v[64:65] neg_lo:[0,1] neg_hi:[0,1]
	s_nop 0
	v_add_f32_e32 v2, v2, v3
	v_mul_f32_e32 v2, 0x3fb8aa3b, v2
	v_exp_f32_e32 v13, v2
	v_cvt_pk_bf16_f32 v2, v11, v10
	v_cvt_pk_bf16_f32 v3, v7, v6
	v_cvt_pk_bf16_f32 v4, v9, v8
	v_cvt_pk_bf16_f32 v5, v51, v50
	v_exp_f32_e32 v6, v14
	s_waitcnt lgkmcnt(7)
	v_mfma_f32_32x32x16_bf16 v[50:65], v[34:37], v[2:5], 0
	v_exp_f32_e32 v7, v38
	v_exp_f32_e32 v8, v40
	v_cvt_pk_bf16_f32 v78, v13, v12
	v_cvt_pk_bf16_f32 v79, v6, v16
	v_cvt_pk_bf16_f32 v80, v7, v41
	v_cvt_pk_bf16_f32 v81, v8, v42
	s_waitcnt lgkmcnt(6)
	v_mfma_f32_32x32x16_bf16 v[34:49], v[18:21], v[2:5], 0
	s_waitcnt lgkmcnt(5)
	v_mfma_f32_32x32x16_bf16 v[50:65], v[30:33], v[78:81], v[50:65]
	s_waitcnt lgkmcnt(4)
	v_mfma_f32_32x32x16_bf16 v[34:49], v[22:25], v[78:81], v[34:49]
	s_waitcnt lgkmcnt(3)
	v_mfma_f32_32x32x16_bf16 v[18:33], v[26:29], v[2:5], 0
	s_waitcnt lgkmcnt(2)
	v_mfma_f32_32x32x16_bf16 v[2:17], v[70:73], v[2:5], 0
	v_add_f32_e64 v70, v124, v122
	v_add_f32_e64 v71, v125, v123
	v_add_f32_e32 v70, v70, v71
	v_cmp_gt_f32_e32 vcc, s88, v70
	s_cmp_eq_u64 vcc, exec
	s_cselect_b64 s[0:1], -1, 0
	s_cmp_eq_u32 s27, 0
	s_waitcnt lgkmcnt(1)
	v_mfma_f32_32x32x16_bf16 v[18:33], v[74:77], v[78:81], v[18:33]
	s_cselect_b64 s[8:9], -1, 0
	s_or_b64 s[0:1], s[8:9], s[0:1]
	s_and_b64 vcc, exec, s[0:1]
	s_waitcnt lgkmcnt(0)
	v_mfma_f32_32x32x16_bf16 v[2:17], v[66:69], v[78:81], v[2:17]
	s_cbranch_vccnz .LBB0_246
	s_and_b32 s0, s14, 0xff
	s_lshl_b32 s0, s0, 5
	s_sub_i32 s84, s0, 32
	v_add_f32_e32 v190, 0, v70
.LBB0_249:
	s_lshl_b64 s[0:1], s[84:85], 12
	v_lshl_add_u64 v[118:119], v[150:151], 0, s[0:1]
	v_add_co_u32_e32 v66, vcc, s81, v118
	global_load_dwordx4 v[70:73], v[118:119], off
	s_nop 0
	v_addc_co_u32_e32 v67, vcc, 0, v119, vcc
	global_load_dwordx4 v[78:81], v[66:67], off
	v_add_co_u32_e32 v66, vcc, s82, v118
	s_add_i32 s8, s27, -1
	s_nop 0
	v_addc_co_u32_e32 v67, vcc, 0, v119, vcc
	global_load_dwordx4 v[122:125], v[66:67], off
	v_add_co_u32_e32 v66, vcc, s76, v118
	s_lshr_b32 s0, s8, 1
	s_nop 0
	v_addc_co_u32_e32 v67, vcc, 0, v119, vcc
	global_load_dwordx4 v[126:129], v[66:67], off
	v_add_co_u32_e32 v66, vcc, s70, v118
	s_mov_b32 s1, s85
	s_nop 0
	v_addc_co_u32_e32 v67, vcc, 0, v119, vcc
	v_add_co_u32_e32 v74, vcc, s80, v118
	s_lshl_b64 s[0:1], s[0:1], 18
	s_nop 0
	v_addc_co_u32_e32 v75, vcc, 0, v119, vcc
	v_add_co_u32_e32 v114, vcc, s71, v118
	s_and_b32 s6, s84, 32
	s_nop 0
	v_addc_co_u32_e32 v115, vcc, 0, v119, vcc
	v_add_co_u32_e32 v118, vcc, s83, v118
	v_lshl_add_u64 v[130:131], v[152:153], 0, s[0:1]
	s_lshl_b32 s0, s6, 12
	s_mov_b32 s1, s85
	v_addc_co_u32_e32 v119, vcc, 0, v119, vcc
	v_lshl_add_u64 v[162:163], v[130:131], 0, s[0:1]
	v_add_co_u32_e32 v142, vcc, s77, v162
	global_load_dwordx4 v[66:69], v[66:67], off
	s_nop 0
	v_addc_co_u32_e32 v143, vcc, 0, v163, vcc
	v_add_co_u32_e32 v158, vcc, s77, v162
	global_load_dwordx4 v[74:77], v[74:75], off
	s_nop 0
	v_addc_co_u32_e32 v159, vcc, 0, v163, vcc
	v_add_co_u32_e32 v166, vcc, s77, v162
	global_load_dwordx4 v[114:117], v[114:115], off
	s_nop 0
	v_addc_co_u32_e32 v167, vcc, 0, v163, vcc
	global_load_dwordx4 v[118:121], v[118:119], off
	s_nop 0
	global_load_dwordx4 v[130:133], v[162:163], off
	global_load_dwordx4 v[134:137], v[162:163], off offset:1024
	global_load_dwordx4 v[138:141], v[162:163], off offset:2048
	s_nop 0
	global_load_dwordx4 v[142:145], v[162:163], off offset:3072
	s_nop 0
	global_load_dwordx4 v[154:157], v[158:159], off
	s_nop 0
	global_load_dwordx4 v[158:161], v[158:159], off offset:1024
	s_nop 0
	global_load_dwordx4 v[162:165], v[166:167], off offset:2048
	s_nop 0
	global_load_dwordx4 v[166:169], v[166:167], off offset:3072
	s_waitcnt vmcnt(15)
	ds_write_b128 v0, v[70:73]
	s_waitcnt vmcnt(14)
	ds_write_b128 v149, v[78:81]
	s_waitcnt vmcnt(13)
	ds_write_b128 v174, v[122:125]
	s_waitcnt vmcnt(12)
	ds_write_b128 v175, v[126:129]
	s_waitcnt vmcnt(11)
	ds_write_b128 v0, v[66:69] offset:4096
	s_waitcnt vmcnt(10)
	ds_write_b128 v176, v[74:77]
	s_waitcnt vmcnt(9)
	ds_write_b128 v177, v[114:117]
	s_waitcnt vmcnt(8)
	ds_write_b128 v178, v[118:121]
	s_waitcnt vmcnt(7)
	ds_write_b128 v183, v[130:133] offset:8192
	s_waitcnt vmcnt(6)
	ds_write_b128 v183, v[134:137] offset:9216
	s_waitcnt vmcnt(5)
	ds_write_b128 v183, v[138:141] offset:10240
	s_waitcnt vmcnt(4)
	ds_write_b128 v183, v[142:145] offset:11264
	s_waitcnt vmcnt(3)
	ds_write_b128 v183, v[154:157] offset:12288
	s_waitcnt vmcnt(2)
	ds_write_b128 v183, v[158:161] offset:13312
	s_waitcnt vmcnt(1)
	ds_write_b128 v183, v[162:165] offset:14336
	s_waitcnt vmcnt(0)
	ds_write_b128 v183, v[166:169] offset:15360
	ds_read_b128 v[66:69], v179
	ds_read_b128 v[114:117], v180
	ds_read_b128 v[118:121], v181
	ds_read_b128 v[122:125], v182
	ds_read_b128 v[126:129], v184
	ds_read_b128 v[130:133], v185
	ds_read_b128 v[134:137], v186
	ds_read_b128 v[138:141], v187
	s_waitcnt lgkmcnt(7)
	v_mfma_f32_32x32x16_bf16 v[66:81], v[66:69], v[82:85], 0
	s_waitcnt lgkmcnt(6)
	v_mfma_f32_32x32x16_bf16 v[66:81], v[114:117], v[86:89], v[66:81]
	s_waitcnt lgkmcnt(5)
	v_mfma_f32_32x32x16_bf16 v[66:81], v[118:121], v[90:93], v[66:81]
	s_waitcnt lgkmcnt(4)
	v_mfma_f32_32x32x16_bf16 v[66:81], v[122:125], v[94:97], v[66:81]
	s_waitcnt lgkmcnt(3)
	v_mfma_f32_32x32x16_bf16 v[66:81], v[126:129], v[98:101], v[66:81]
	s_waitcnt lgkmcnt(2)
	v_mfma_f32_32x32x16_bf16 v[66:81], v[130:133], v[102:105], v[66:81]
	s_waitcnt lgkmcnt(1)
	v_mfma_f32_32x32x16_bf16 v[66:81], v[134:137], v[106:109], v[66:81]
	s_waitcnt lgkmcnt(0)
	v_mfma_f32_32x32x16_bf16 v[66:81], v[138:141], v[110:113], v[66:81]
	ds_read_b128 v[114:117], v189 offset:14336
	ds_read_b128 v[118:121], v188 offset:14336
	ds_read_b128 v[122:125], v189 offset:12288
	ds_read_b128 v[126:129], v188 offset:12288
	ds_read_b128 v[130:133], v189 offset:10240
	ds_read_b128 v[134:137], v188 offset:10240
	ds_read_b128 v[138:141], v189 offset:8192
	ds_read_b128 v[142:145], v188 offset:8192
	s_nop 3
	v_mul_f32_e64 v155, |v66|, s79
	v_mul_f32_e64 v157, |v67|, s79
	v_exp_f32_e32 v155, v155
	v_exp_f32_e32 v157, v157
	v_max_f32_e32 v154, v66, v66
	v_max_f32_e32 v154, 0, v154
	v_add_f32_e32 v155, 1.0, v155
	v_add_f32_e32 v157, 1.0, v157
	v_log_f32_e32 v156, v155
	v_log_f32_e32 v157, v157
	v_max_f32_e32 v155, v67, v67
	v_max_f32_e32 v155, 0, v155
	v_mul_f32_e64 v159, |v69|, s79
	v_pk_fma_f32 v[156:157], v[156:157], s[74:75], v[154:155] op_sel_hi:[1,0,1]
	v_mul_f32_e64 v155, |v68|, s79
	v_exp_f32_e32 v155, v155
	v_exp_f32_e32 v159, v159
	v_max_f32_e32 v154, v68, v68
	v_max_f32_e32 v154, 0, v154
	v_add_f32_e32 v155, 1.0, v155
	v_add_f32_e32 v159, 1.0, v159
	v_log_f32_e32 v158, v155
	v_log_f32_e32 v159, v159
	v_max_f32_e32 v155, v69, v69
	v_max_f32_e32 v155, 0, v155
	v_sub_f32_e64 v162, -v156, v157
	v_pk_fma_f32 v[160:161], v[158:159], s[74:75], v[154:155] op_sel_hi:[1,0,1]
	v_mul_f32_e64 v155, |v70|, s79
	v_mul_f32_e64 v159, |v71|, s79
	v_exp_f32_e32 v155, v155
	v_exp_f32_e32 v159, v159
	v_sub_f32_e32 v154, v162, v160
	v_sub_f32_e32 v162, v154, v161
	v_add_f32_e32 v155, 1.0, v155
	v_add_f32_e32 v159, 1.0, v159
	v_log_f32_e32 v158, v155
	v_log_f32_e32 v159, v159
	v_max_f32_e32 v154, v70, v70
	v_max_f32_e32 v155, v71, v71
	v_max_f32_e32 v154, 0, v154
	v_max_f32_e32 v155, 0, v155
	v_pk_fma_f32 v[164:165], v[158:159], s[74:75], v[154:155] op_sel_hi:[1,0,1]
	v_mul_f32_e64 v155, |v72|, s79
	v_mul_f32_e64 v159, |v73|, s79
	v_exp_f32_e32 v155, v155
	v_exp_f32_e32 v159, v159
	v_sub_f32_e32 v154, v162, v164
	v_sub_f32_e32 v162, v154, v165
	v_add_f32_e32 v155, 1.0, v155
	v_add_f32_e32 v159, 1.0, v159
	v_log_f32_e32 v158, v155
	v_log_f32_e32 v159, v159
	v_max_f32_e32 v154, v72, v72
	v_max_f32_e32 v155, v73, v73
	v_max_f32_e32 v154, 0, v154
	v_max_f32_e32 v155, 0, v155
	v_pk_fma_f32 v[168:169], v[158:159], s[74:75], v[154:155] op_sel_hi:[1,0,1]
	s_nop 0
	v_sub_f32_e32 v191, v73, v169
	v_max_f32_e32 v73, v74, v74
	v_max_f32_e32 v158, 0, v73
	v_mul_f32_e64 v73, |v74|, s79
	v_exp_f32_e32 v73, v73
	v_sub_f32_e32 v154, v162, v168
	v_sub_f32_e32 v155, v154, v169
	v_max_f32_e32 v154, v76, v76
	v_add_f32_e32 v73, 1.0, v73
	v_log_f32_e32 v162, v73
	v_max_f32_e32 v73, v75, v75
	v_max_f32_e32 v159, 0, v73
	v_mul_f32_e64 v73, |v75|, s79
	v_exp_f32_e32 v73, v73
	s_nop 0
	v_add_f32_e32 v73, 1.0, v73
	v_log_f32_e32 v163, v73
	s_nop 0
	v_pk_fma_f32 v[158:159], v[162:163], s[74:75], v[158:159] op_sel_hi:[1,0,1]
	v_max_f32_e32 v162, 0, v154
	v_mul_f32_e64 v154, |v76|, s79
	v_exp_f32_e32 v154, v154
	v_sub_f32_e64 v73, -v158, v159
	v_add_f32_e32 v154, 1.0, v154
	v_log_f32_e32 v166, v154
	v_max_f32_e32 v154, v77, v77
	v_max_f32_e32 v163, 0, v154
	v_mul_f32_e64 v154, |v77|, s79
	v_exp_f32_e32 v154, v154
	s_nop 0
	v_add_f32_e32 v154, 1.0, v154
	v_log_f32_e32 v167, v154
	v_max_f32_e32 v154, v78, v78
	v_pk_fma_f32 v[162:163], v[166:167], s[74:75], v[162:163] op_sel_hi:[1,0,1]
	v_max_f32_e32 v166, 0, v154
	v_mul_f32_e64 v154, |v78|, s79
	v_exp_f32_e32 v154, v154
	v_sub_f32_e32 v73, v73, v162
	v_sub_f32_e32 v73, v73, v163
	v_add_f32_e32 v154, 1.0, v154
	v_log_f32_e32 v170, v154
	v_max_f32_e32 v154, v79, v79
	v_max_f32_e32 v167, 0, v154
	v_mul_f32_e64 v154, |v79|, s79
	v_exp_f32_e32 v154, v154
	s_nop 0
	v_add_f32_e32 v154, 1.0, v154
	v_log_f32_e32 v171, v154
	v_max_f32_e32 v154, v80, v80
	v_pk_fma_f32 v[166:167], v[170:171], s[74:75], v[166:167] op_sel_hi:[1,0,1]
	v_max_f32_e32 v170, 0, v154
	v_mul_f32_e64 v154, |v80|, s79
	v_exp_f32_e32 v154, v154
	v_sub_f32_e32 v73, v73, v166
	v_sub_f32_e32 v73, v73, v167
	v_add_f32_e32 v154, 1.0, v154
	v_log_f32_e32 v172, v154
	v_max_f32_e32 v154, v81, v81
	v_max_f32_e32 v171, 0, v154
	v_mul_f32_e64 v154, |v81|, s79
	v_exp_f32_e32 v154, v154
	s_nop 0
	v_add_f32_e32 v154, 1.0, v154
	v_log_f32_e32 v173, v154
	s_nop 0
	v_pk_fma_f32 v[172:173], v[172:173], s[74:75], v[170:171] op_sel_hi:[1,0,1]
	s_nop 0
	v_sub_f32_e32 v73, v73, v172
	v_sub_f32_e32 v196, v81, v173
	v_sub_f32_e32 v171, v73, v173
	v_mov_b32_e32 v73, v155
	v_mov_b32_e32 v81, v155
	s_nop 1
	v_permlane32_swap_b32_e32 v73, v81
	v_cndmask_b32_e64 v154, v73, v81, s[38:39]
	v_mov_b32_e32 v73, v171
	v_mov_b32_e32 v81, v171
	s_nop 1
	v_permlane32_swap_b32_e32 v73, v81
	v_cndmask_b32_e64 v170, v73, v81, s[38:39]
	v_add_f32_e32 v73, v171, v154
	v_cndmask_b32_e64 v73, v171, v73, s[42:43]
	v_add_f32_e32 v73, v73, v170
	v_add_f32_e32 v73, v190, v73
	v_pk_add_f32 v[192:193], v[72:73], v[168:169] neg_lo:[0,1] neg_hi:[0,1]
	v_pk_mov_b32 v[168:169], v[164:165], v[168:169] op_sel:[1,0]
	v_add_f32_e32 v72, v192, v193
	v_mov_b32_e32 v192, v71
	v_pk_add_f32 v[168:169], v[192:193], v[168:169] neg_lo:[0,1] neg_hi:[0,1]
	v_add_f32_e32 v81, v191, v73
	v_add_f32_e32 v71, v168, v169
	v_mul_f32_e32 v71, 0x3fb8aa3b, v71
	v_exp_f32_e32 v73, v71
	v_mov_b32_e32 v71, v169
	v_pk_add_f32 v[168:169], v[70:71], v[164:165] neg_lo:[0,1] neg_hi:[0,1]
	v_pk_mov_b32 v[164:165], v[160:161], v[164:165] op_sel:[1,0]
	v_add_f32_e32 v70, v168, v169
	v_mov_b32_e32 v168, v69
	v_pk_add_f32 v[164:165], v[168:169], v[164:165] neg_lo:[0,1] neg_hi:[0,1]
	v_mul_f32_e32 v81, 0x3fb8aa3b, v81
	v_add_f32_e32 v69, v164, v165
	v_mul_f32_e32 v69, 0x3fb8aa3b, v69
	v_exp_f32_e32 v71, v69
	v_mov_b32_e32 v69, v165
	v_pk_add_f32 v[164:165], v[68:69], v[160:161] neg_lo:[0,1] neg_hi:[0,1]
	v_pk_mov_b32 v[160:161], v[156:157], v[160:161] op_sel:[1,0]
	v_add_f32_e32 v68, v164, v165
	v_mov_b32_e32 v164, v67
	v_pk_add_f32 v[160:161], v[164:165], v[160:161] neg_lo:[0,1] neg_hi:[0,1]
	v_exp_f32_e32 v191, v81
	v_add_f32_e32 v67, v160, v161
	v_mul_f32_e32 v67, 0x3fb8aa3b, v67
	v_exp_f32_e32 v69, v67
	v_mov_b32_e32 v67, v161
	v_pk_add_f32 v[66:67], v[66:67], v[156:157] neg_lo:[0,1] neg_hi:[0,1]
	v_pk_mov_b32 v[160:161], v[166:167], v[172:173] op_sel:[1,0]
	v_add_f32_e32 v66, v66, v67
	v_mul_f32_e32 v66, 0x3fb8aa3b, v66
	v_exp_f32_e32 v67, v66
	v_cndmask_b32_e64 v66, 0, v170, s[42:43]
	v_add_f32_e32 v81, v190, v66
	v_pk_add_f32 v[156:157], v[80:81], v[172:173] neg_lo:[0,1] neg_hi:[0,1]
	v_add_f32_e32 v66, v196, v81
	v_add_f32_e32 v80, v156, v157
	v_mov_b32_e32 v156, v79
	v_pk_add_f32 v[156:157], v[156:157], v[160:161] neg_lo:[0,1] neg_hi:[0,1]
	v_mul_f32_e32 v72, 0x3fb8aa3b, v72
	v_add_f32_e32 v79, v156, v157
	v_mul_f32_e32 v79, 0x3fb8aa3b, v79
	v_exp_f32_e32 v81, v79
	v_mov_b32_e32 v79, v157
	v_pk_add_f32 v[78:79], v[78:79], v[166:167] neg_lo:[0,1] neg_hi:[0,1]
	v_pk_mov_b32 v[156:157], v[162:163], v[166:167] op_sel:[1,0]
	v_add_f32_e32 v78, v78, v79
	v_mul_f32_e32 v78, 0x3fb8aa3b, v78
	v_exp_f32_e32 v160, v78
	v_mov_b32_e32 v78, v77
	v_pk_add_f32 v[78:79], v[78:79], v[156:157] neg_lo:[0,1] neg_hi:[0,1]
	v_mul_f32_e32 v70, 0x3fb8aa3b, v70
	v_add_f32_e32 v77, v78, v79
	v_mul_f32_e32 v77, 0x3fb8aa3b, v77
	v_exp_f32_e32 v156, v77
	v_mov_b32_e32 v77, v79
	v_pk_add_f32 v[76:77], v[76:77], v[162:163] neg_lo:[0,1] neg_hi:[0,1]
	v_pk_mov_b32 v[78:79], v[158:159], v[162:163] op_sel:[1,0]
	v_add_f32_e32 v76, v76, v77
	v_mul_f32_e32 v76, 0x3fb8aa3b, v76
	v_exp_f32_e32 v157, v76
	v_mov_b32_e32 v76, v75
	v_pk_add_f32 v[76:77], v[76:77], v[78:79] neg_lo:[0,1] neg_hi:[0,1]
	v_mul_f32_e32 v68, 0x3fb8aa3b, v68
	v_add_f32_e32 v75, v76, v77
	v_mul_f32_e32 v75, 0x3fb8aa3b, v75
	v_exp_f32_e32 v72, v72
	v_exp_f32_e32 v70, v70
	v_exp_f32_e32 v68, v68
	v_exp_f32_e32 v161, v75
	v_mov_b32_e32 v75, v77
	v_cvt_pk_bf16_f32 v76, v67, v69
	v_cvt_pk_bf16_f32 v77, v68, v71
	v_cvt_pk_bf16_f32 v78, v70, v73
	v_cvt_pk_bf16_f32 v79, v72, v191
	v_pk_add_f32 v[74:75], v[74:75], v[158:159] neg_lo:[0,1] neg_hi:[0,1]
	s_waitcnt lgkmcnt(0)
	v_mfma_f32_32x32x16_bf16 v[50:65], v[142:145], v[76:79], v[50:65]
	v_add_f32_e32 v74, v74, v75
	v_mul_f32_e32 v74, 0x3fb8aa3b, v74
	v_mul_f32_e32 v66, 0x3fb8aa3b, v66
	v_mul_f32_e32 v80, 0x3fb8aa3b, v80
	v_exp_f32_e32 v158, v74
	v_pk_add_f32 v[74:75], v[154:155], v[170:171]
	v_exp_f32_e32 v66, v66
	v_mfma_f32_32x32x16_bf16 v[34:49], v[134:137], v[76:79], v[34:49]
	v_exp_f32_e32 v80, v80
	v_add_f32_e32 v74, v74, v75
	v_cvt_pk_bf16_f32 v68, v158, v161
	v_cvt_pk_bf16_f32 v69, v157, v156
	v_cvt_pk_bf16_f32 v70, v160, v81
	v_cvt_pk_bf16_f32 v71, v80, v66
	v_add_f32_e32 v190, v190, v74
	v_mfma_f32_32x32x16_bf16 v[18:33], v[126:129], v[76:79], v[18:33]
	v_cmp_gt_f32_e32 vcc, s88, v190
	s_cmp_lg_u64 vcc, exec
	s_cselect_b64 s[0:1], -1, 0
	s_cmp_gt_u32 s27, 1
	s_cselect_b64 s[10:11], -1, 0
	s_and_b64 s[0:1], s[0:1], s[10:11]
	s_sub_i32 s84, s84, 32
	v_mfma_f32_32x32x16_bf16 v[2:17], v[118:121], v[76:79], v[2:17]
	s_and_b64 vcc, exec, s[0:1]
	s_mov_b32 s27, s8
	v_mfma_f32_32x32x16_bf16 v[50:65], v[138:141], v[68:71], v[50:65]
	v_mfma_f32_32x32x16_bf16 v[34:49], v[130:133], v[68:71], v[34:49]
	v_mfma_f32_32x32x16_bf16 v[18:33], v[122:125], v[68:71], v[18:33]
	v_mfma_f32_32x32x16_bf16 v[2:17], v[114:117], v[68:71], v[2:17]
	s_cbranch_vccnz .LBB0_249
	s_branch .LBB0_246
